# GQA attention K loop: staging addresses hoisted (SGPR base + invariant lane offset), two barriers per KV tile with the two 4-wave halves half a tile apart (softmax VALU beside the other half's MFMA)
# speedup vs baseline: 1.0017x; 1.0017x over previous
; template <int DK, int DV, int MODE, int QB, bool PACK = false>
; DI void attn_item(const AttArgs& a, int q0, int t_lo, int t_hi) {
;     ...
;   bf16x8 qf[QB][NKS];
; #pragma unroll
;   for (int qb = 0; qb < QB; ++qb) {
;     const bf16_t* qp = a.q + hg * DK + (size_t)(wq0 + qb * 32 + r) * a.ldq + h * 8;
; #pragma unroll
;     for (int s = 0; s < NKS; ++s) qf[qb][s] = *(const bf16x8*)(qp + s * 16);
;   }
;   f32x16 o[QB][NDB];
;   float m[QB], lsum[QB];
; #pragma unroll
;   for (int qb = 0; qb < QB; ++qb) {
;     m[qb] = -1e30f; lsum[qb] = 0.f;
; #pragma unroll
;     for (int d = 0; d < NDB; ++d)
; #pragma unroll
;       for (int i = 0; i < 16; ++i) o[qb][d][i] = 0.f;
;   }
;   u32x4 kr[NKL], vr[NVL];
;   att_gload<DK, DV, MODE>(a, t_lo, kr, vr);
;   att_swrite<DK, DV>(0, kr, vr);
;   if (t_lo + 1 < t_hi) att_gload<DK, DV, MODE>(a, t_lo + 1, kr, vr);
;   __syncthreads();
;   const float scale = a.scale;
;   const float cexp = (MODE == 2) ? LOG2E : a.scale * LOG2E;
;   const int vq = (l & 15) >> 2, vp = l & 3, vblk = (l >> 4) & 1;
.LBB0_834:
	s_or_b64 exec, exec, s[4:5]
	s_waitcnt vmcnt(1)
	v_add_u32_e32 v8, v12, v14
	s_waitcnt vmcnt(0)
	ds_write_b128 v8, v[4:7] offset:9216
	v_mov_b32_e32 v8, v224
	s_mov_b32 s4, 0x40000
	v_min_i32_e32 v5, 0x1ff, v8
	v_ashrrev_i32_e32 v4, 31, v5
	v_lshrrev_b32_e32 v4, 29, v4
	v_add_u32_e32 v6, v5, v4
	v_ashrrev_i32_e32 v4, 3, v6
	v_and_b32_e32 v6, 0x1ffffff8, v6
	v_sub_u32_e32 v6, v5, v6
	v_ashrrev_i32_e32 v5, 31, v4
	v_lshlrev_b64 v[4:5], 12, v[4:5]
	v_lshlrev_b32_e32 v6, 3, v6
	v_ashrrev_i32_e32 v7, 31, v6
	v_lshl_add_u64 v[4:5], s[2:3], 0, v[4:5]
	v_lshl_add_u64 v[4:5], v[6:7], 1, v[4:5]
	v_ashrrev_i32_e32 v6, 31, v8
	v_lshrrev_b32_e32 v6, 29, v6
	v_add_u32_e32 v7, v8, v6
	v_ashrrev_i32_e32 v6, 3, v7
	v_and_b32_e32 v7, 0x1ffffff8, v7
	v_sub_u32_e32 v8, v8, v7
	v_ashrrev_i32_e32 v7, 31, v6
	v_lshlrev_b64 v[6:7], 12, v[6:7]
	v_lshlrev_b32_e32 v8, 3, v8
	v_add_co_u32_e32 v4, vcc, s4, v4
	v_ashrrev_i32_e32 v9, 31, v8
	v_lshl_add_u64 v[6:7], s[2:3], 0, v[6:7]
	v_addc_co_u32_e32 v5, vcc, 0, v5, vcc
	v_lshl_add_u64 v[6:7], v[8:9], 1, v[6:7]
	v_add_co_u32_e32 v6, vcc, s4, v6
	v_lshlrev_b32_e32 v189, 3, v3
	s_nop 0
	v_addc_co_u32_e32 v7, vcc, 0, v7, vcc
	global_load_dwordx4 v[176:179], v[4:5], off offset:1024
	global_load_dwordx4 v[180:183], v[6:7], off offset:1280
	v_bfe_u32 v4, v1, 2, 2
	v_and_b32_e32 v5, 16, v1
	v_lshlrev_b32_e32 v1, 2, v1
	v_lshl_or_b32 v3, v3, 2, v4
	v_and_or_b32 v1, v1, 12, v5
	v_mov_b32_e32 v14, v2
	v_mov_b32_e32 v15, v2
	v_lshlrev_b32_e32 v204, 1, v1
	v_mul_u32_u24_e32 v208, 0x90, v0
	v_mul_u32_u24_e32 v205, 0x90, v3
	v_mov_b32_e32 v0, v2
	v_mov_b32_e32 v1, v2
	v_mov_b32_e32 v3, v2
	v_mov_b32_e32 v4, v2
	v_mov_b32_e32 v5, v2
	v_mov_b32_e32 v6, v2
	v_mov_b32_e32 v7, v2
	v_mov_b32_e32 v8, v2
	v_mov_b32_e32 v9, v2
	v_mov_b32_e32 v10, v2
	v_mov_b32_e32 v11, v2
	v_mov_b32_e32 v12, v2
	v_mov_b32_e32 v13, v2
	v_mov_b64_e32 v[30:31], v[14:15]
	v_mov_b64_e32 v[46:47], v[14:15]
	v_mov_b64_e32 v[62:63], v[14:15]
	v_mov_b64_e32 v[78:79], v[14:15]
	s_lshl_b32 s8, s6, 6
	s_mov_b32 s9, 0
	v_mov_b32_e32 v206, 0
	v_mov_b32_e32 v191, 0xf149f2ca
	s_add_u32 s4, s2, 0x80000
	s_addc_u32 s5, s3, 0
	v_lshrrev_b32_e32 v210, 3, v224
	v_and_b32_e32 v211, 7, v224
	v_lshlrev_b32_e32 v212, 12, v210
	v_lshl_or_b32 v212, v211, 4, v212
	v_mul_u32_u24_e32 v210, 0x90, v210
	v_lshl_add_u32 v210, v211, 4, v210
	v_mov_b64_e32 v[28:29], v[12:13]
	v_mov_b64_e32 v[26:27], v[10:11]
	v_mov_b64_e32 v[24:25], v[8:9]
	v_mov_b64_e32 v[22:23], v[6:7]
	v_mov_b64_e32 v[20:21], v[4:5]
	v_mov_b64_e32 v[18:19], v[2:3]
	v_mov_b64_e32 v[16:17], v[0:1]
	v_mov_b64_e32 v[44:45], v[12:13]
	v_mov_b64_e32 v[42:43], v[10:11]
	v_mov_b64_e32 v[40:41], v[8:9]
	v_mov_b64_e32 v[38:39], v[6:7]
	v_mov_b64_e32 v[36:37], v[4:5]
	v_mov_b64_e32 v[34:35], v[2:3]
	v_mov_b64_e32 v[32:33], v[0:1]
	v_mov_b64_e32 v[60:61], v[12:13]
	v_mov_b64_e32 v[58:59], v[10:11]
	v_mov_b64_e32 v[56:57], v[8:9]
	v_mov_b64_e32 v[54:55], v[6:7]
	v_mov_b64_e32 v[52:53], v[4:5]
	v_mov_b64_e32 v[50:51], v[2:3]
	v_mov_b64_e32 v[48:49], v[0:1]
	v_mov_b64_e32 v[76:77], v[12:13]
	v_mov_b64_e32 v[74:75], v[10:11]
	v_mov_b64_e32 v[72:73], v[8:9]
	v_mov_b64_e32 v[70:71], v[6:7]
	v_mov_b64_e32 v[68:69], v[4:5]
	v_mov_b64_e32 v[66:67], v[2:3]
	v_mov_b64_e32 v[64:65], v[0:1]
	v_mov_b32_e32 v1, 0xf149f2ca
	v_mov_b32_e32 v207, 0
	s_waitcnt lgkmcnt(0)
	s_barrier
	v_readfirstlane_b32 s7, v224
	s_cmpk_lt_u32 s7, 0x100
	s_cbranch_scc1 .Lpp0_entry
	s_barrier

; template <int DK, int DV>
; DI void att_swrite(int buf, const u32x4 (&kr)[(64 * (DK / 8) + NT - 1) / NT], const u32x4 (&vr)[(64 * (DV / 8) + NT - 1) / NT]) {
;   constexpr int CK = DK / 8, CV = DV / 8;
;   constexpr int KST = DK * 2 + 16, VST = DV * 2 + 16;
;   constexpr int KBYTES = 64 * KST, VBYTES = 64 * VST, BUFB = KBYTES + VBYTES;
;   constexpr int NKL = (64 * CK + NT - 1) / NT, NVL = (64 * CV + NT - 1) / NT;
;   const int t = tid_opaque();
; #pragma unroll
; template <int DK, int DV, int MODE, int QB, bool PACK = false>
; DI void attn_item(const AttArgs& a, int q0, int t_lo, int t_hi) {
;     ...
;         const float mc = -m[qb] * cexp;
;         const f32x2 c2 = {cexp, cexp}, mc2 = {mc, mc};
;         f32x2 ps2 = {0.f, 0.f};
; #pragma unroll
;         for (int kb = 0; kb < 2; ++kb)
; #pragma unroll
;           for (int i = 0; i < 16; i += 2) {
;             const f32x2 sv = {s[qb][kb][i], s[qb][kb][i + 1]};
;             const f32x2 e2 = sv * c2 + mc2;
;             f32x2 pv = {fexp2(e2[0]), fexp2(e2[1])};
;             if constexpr (MODE == 1 || MODE == 2) {
;               pv[0] = (sv[0] > -1e29f) ? pv[0] : 0.f;
;               pv[1] = (sv[1] > -1e29f) ? pv[1] : 0.f;
;             }
;             s[qb][kb][i] = pv[0];
;             s[qb][kb][i + 1] = pv[1];
;             ps2 += pv;
;           }
;         lsum[qb] += ps2[0] + ps2[1];
;       }
; #pragma unroll
;       for (int qb = 0; qb < QB; ++qb)
; #pragma unroll
;         for (int kb = 0; kb < 2; ++kb)
; #pragma unroll
;           for (int st = 0; st < 2; ++st) {
;             u32x4 pk;
;             pk[0] = pack2(s[qb][kb][8 * st + 0], s[qb][kb][8 * st + 1]);
;             pk[1] = pack2(s[qb][kb][8 * st + 2], s[qb][kb][8 * st + 3]);
;             pk[2] = pack2(s[qb][kb][8 * st + 4], s[qb][kb][8 * st + 5]);
;             pk[3] = pack2(s[qb][kb][8 * st + 6], s[qb][kb][8 * st + 7]);
;             const bf16x8 pf = __builtin_bit_cast(bf16x8, pk);
;             const unsigned char* vrow = Vb + (kb * 32 + 16 * st + 4 * h + vq) * VST + (16 * vblk + 4 * vp) * 2;
; #pragma unroll
;             for (int d = 0; d < NDB; ++d) {
;               s16x4 lo = __builtin_amdgcn_ds_read_tr16_b64_v4i16((s16x4 __attribute__((address_space(3)))*)(vrow + d * 64));
;               s16x4 hi = __builtin_amdgcn_ds_read_tr16_b64_v4i16((s16x4 __attribute__((address_space(3)))*)(vrow + 8 * VST + d * 64));
.LBB0_835:
	s_barrier
	s_cmp_gt_u32 s9, 29
	s_cbranch_scc1 .Lpp0_last
	s_waitcnt vmcnt(1)
	ds_write_b128 v211, v[180:183] offset:9216
	global_load_dwordx4 v[180:183], v212, s[4:5] offset:1280
	s_branch .Lpp0_cont
.Lpp0_last:
	s_waitcnt vmcnt(0)
	ds_write_b128 v211, v[180:183] offset:9216
.Lpp0_cont:
	v_mul_f32_e32 v0, 0xbe38aa3b, v1
	v_pk_fma_f32 v[4:5], v[128:129], s[16:17], v[0:1] op_sel_hi:[1,0,0]
	v_pk_fma_f32 v[6:7], v[130:131], s[16:17], v[0:1] op_sel_hi:[1,0,0]
	v_exp_f32_e32 v4, v4
	v_exp_f32_e32 v5, v5
	v_exp_f32_e32 v6, v6
	v_exp_f32_e32 v7, v7
	v_pk_fma_f32 v[14:15], v[136:137], s[16:17], v[0:1] op_sel_hi:[1,0,0]
	v_pk_add_f32 v[8:9], v[4:5], 0 op_sel_hi:[1,0]
	v_exp_f32_e32 v196, v14
	v_pk_add_f32 v[10:11], v[6:7], v[8:9]
	v_pk_fma_f32 v[8:9], v[132:133], s[16:17], v[0:1] op_sel_hi:[1,0,0]
	v_exp_f32_e32 v197, v15
	v_exp_f32_e32 v8, v8
	v_exp_f32_e32 v9, v9
	v_pk_fma_f32 v[14:15], v[138:139], s[16:17], v[0:1] op_sel_hi:[1,0,0]
	v_mul_f32_e32 v190, 0xbe38aa3b, v191
	v_exp_f32_e32 v198, v14
	v_pk_add_f32 v[12:13], v[8:9], v[10:11]
	v_pk_fma_f32 v[10:11], v[134:135], s[16:17], v[0:1] op_sel_hi:[1,0,0]
	v_exp_f32_e32 v199, v15
	v_exp_f32_e32 v10, v10
	v_exp_f32_e32 v11, v11
	v_pk_fma_f32 v[14:15], v[140:141], s[16:17], v[0:1] op_sel_hi:[1,0,0]
	v_add3_u32 v209, s6, v204, v205
	v_exp_f32_e32 v200, v14
	v_exp_f32_e32 v201, v15
	v_pk_fma_f32 v[14:15], v[142:143], s[16:17], v[0:1] op_sel_hi:[1,0,0]
	v_pk_add_f32 v[12:13], v[10:11], v[12:13]
	v_exp_f32_e32 v202, v14
	v_exp_f32_e32 v203, v15
	v_pk_fma_f32 v[14:15], v[112:113], s[16:17], v[0:1] op_sel_hi:[1,0,0]
	v_pk_add_f32 v[12:13], v[196:197], v[12:13]
	v_exp_f32_e32 v140, v14
	v_exp_f32_e32 v141, v15
	v_pk_fma_f32 v[14:15], v[114:115], s[16:17], v[0:1] op_sel_hi:[1,0,0]
	v_pk_add_f32 v[12:13], v[198:199], v[12:13]
	v_exp_f32_e32 v142, v14
	v_exp_f32_e32 v143, v15
	v_pk_fma_f32 v[14:15], v[116:117], s[16:17], v[0:1] op_sel_hi:[1,0,0]
	v_pk_add_f32 v[12:13], v[200:201], v[12:13]
	v_exp_f32_e32 v192, v14
	v_exp_f32_e32 v193, v15
	v_pk_fma_f32 v[14:15], v[118:119], s[16:17], v[0:1] op_sel_hi:[1,0,0]
	v_pk_add_f32 v[12:13], v[202:203], v[12:13]
	v_exp_f32_e32 v194, v14
	v_exp_f32_e32 v195, v15
	v_pk_fma_f32 v[14:15], v[120:121], s[16:17], v[0:1] op_sel_hi:[1,0,0]
	v_pk_add_f32 v[12:13], v[140:141], v[12:13]
	v_exp_f32_e32 v132, v14
	v_exp_f32_e32 v133, v15
	v_pk_fma_f32 v[14:15], v[122:123], s[16:17], v[0:1] op_sel_hi:[1,0,0]
	v_pk_add_f32 v[12:13], v[142:143], v[12:13]
	v_exp_f32_e32 v134, v14
	v_exp_f32_e32 v135, v15
	v_pk_fma_f32 v[14:15], v[124:125], s[16:17], v[0:1] op_sel_hi:[1,0,0]
	v_pk_add_f32 v[12:13], v[192:193], v[12:13]
	v_exp_f32_e32 v136, v14
	v_exp_f32_e32 v137, v15
	v_pk_fma_f32 v[14:15], v[126:127], s[16:17], v[0:1] op_sel_hi:[1,0,0]
	v_pk_add_f32 v[12:13], v[194:195], v[12:13]
	v_exp_f32_e32 v138, v14
	v_exp_f32_e32 v139, v15
	v_pk_add_f32 v[12:13], v[132:133], v[12:13]
	v_pk_fma_f32 v[14:15], v[98:99], s[16:17], v[190:191] op_sel_hi:[1,0,0]
	v_pk_add_f32 v[12:13], v[134:135], v[12:13]
	v_exp_f32_e32 v126, v14
	v_pk_add_f32 v[12:13], v[136:137], v[12:13]
	v_exp_f32_e32 v127, v15
	v_pk_add_f32 v[12:13], v[138:139], v[12:13]
	v_pk_fma_f32 v[14:15], v[100:101], s[16:17], v[190:191] op_sel_hi:[1,0,0]
	v_add_f32_e32 v12, v12, v13
	v_add_f32_e32 v207, v207, v12
	v_pk_fma_f32 v[12:13], v[96:97], s[16:17], v[190:191] op_sel_hi:[1,0,0]
	v_exp_f32_e32 v128, v14
	v_exp_f32_e32 v124, v12
	v_exp_f32_e32 v125, v13
	v_exp_f32_e32 v129, v15
	v_pk_fma_f32 v[14:15], v[102:103], s[16:17], v[190:191] op_sel_hi:[1,0,0]
	v_cvt_pk_bf16_f32 v132, v132, v133
	v_exp_f32_e32 v130, v14
	v_exp_f32_e32 v131, v15
	v_pk_fma_f32 v[14:15], v[104:105], s[16:17], v[190:191] op_sel_hi:[1,0,0]
	v_pk_add_f32 v[12:13], v[124:125], 0 op_sel_hi:[1,0]
	v_exp_f32_e32 v116, v14
	v_exp_f32_e32 v117, v15
	v_pk_fma_f32 v[14:15], v[106:107], s[16:17], v[190:191] op_sel_hi:[1,0,0]
	v_pk_add_f32 v[12:13], v[126:127], v[12:13]
	v_exp_f32_e32 v118, v14
	v_exp_f32_e32 v119, v15
	v_pk_fma_f32 v[14:15], v[108:109], s[16:17], v[190:191] op_sel_hi:[1,0,0]
	v_pk_add_f32 v[12:13], v[128:129], v[12:13]
	v_exp_f32_e32 v120, v14
	v_exp_f32_e32 v121, v15
	v_pk_fma_f32 v[14:15], v[110:111], s[16:17], v[190:191] op_sel_hi:[1,0,0]
	v_pk_add_f32 v[12:13], v[130:131], v[12:13]
	v_exp_f32_e32 v122, v14
	v_exp_f32_e32 v123, v15
	v_pk_fma_f32 v[14:15], v[80:81], s[16:17], v[190:191] op_sel_hi:[1,0,0]
	v_pk_add_f32 v[12:13], v[116:117], v[12:13]
	v_exp_f32_e32 v108, v14
	v_exp_f32_e32 v109, v15
	v_pk_fma_f32 v[14:15], v[82:83], s[16:17], v[190:191] op_sel_hi:[1,0,0]
	v_pk_add_f32 v[12:13], v[118:119], v[12:13]
	v_exp_f32_e32 v110, v14
	v_exp_f32_e32 v111, v15
	v_pk_fma_f32 v[14:15], v[84:85], s[16:17], v[190:191] op_sel_hi:[1,0,0]
	v_pk_add_f32 v[12:13], v[120:121], v[12:13]
	v_exp_f32_e32 v112, v14
	v_exp_f32_e32 v113, v15
	v_pk_fma_f32 v[14:15], v[86:87], s[16:17], v[190:191] op_sel_hi:[1,0,0]
	v_pk_add_f32 v[12:13], v[122:123], v[12:13]
	v_exp_f32_e32 v114, v14
	v_exp_f32_e32 v115, v15
	v_pk_fma_f32 v[14:15], v[88:89], s[16:17], v[190:191] op_sel_hi:[1,0,0]
	v_pk_add_f32 v[12:13], v[108:109], v[12:13]
	v_exp_f32_e32 v100, v14
	v_exp_f32_e32 v101, v15
	v_pk_fma_f32 v[14:15], v[90:91], s[16:17], v[190:191] op_sel_hi:[1,0,0]
	v_pk_add_f32 v[12:13], v[110:111], v[12:13]
	v_exp_f32_e32 v102, v14
	v_exp_f32_e32 v103, v15
	v_pk_fma_f32 v[14:15], v[92:93], s[16:17], v[190:191] op_sel_hi:[1,0,0]
	v_pk_add_f32 v[12:13], v[112:113], v[12:13]
	v_exp_f32_e32 v104, v14
	v_exp_f32_e32 v105, v15
	v_pk_fma_f32 v[14:15], v[94:95], s[16:17], v[190:191] op_sel_hi:[1,0,0]
	v_pk_add_f32 v[12:13], v[114:115], v[12:13]
	v_exp_f32_e32 v106, v14
	v_exp_f32_e32 v107, v15
	v_pk_add_f32 v[12:13], v[100:101], v[12:13]
	v_cvt_pk_bf16_f32 v14, v8, v9
	v_pk_add_f32 v[12:13], v[102:103], v[12:13]
	v_cvt_pk_bf16_f32 v15, v10, v11
	v_pk_add_f32 v[12:13], v[104:105], v[12:13]
	ds_read_b64_tr_b16 v[8:9], v209 offset:9216
	ds_read_b64_tr_b16 v[10:11], v209 offset:10368
	v_pk_add_f32 v[12:13], v[106:107], v[12:13]
	v_cvt_pk_bf16_f32 v124, v124, v125
	v_add_f32_e32 v12, v12, v13
	v_add_f32_e32 v206, v206, v12
	v_cvt_pk_bf16_f32 v12, v4, v5
	v_cvt_pk_bf16_f32 v13, v6, v7
	ds_read_b64_tr_b16 v[4:5], v209 offset:9280
	ds_read_b64_tr_b16 v[6:7], v209 offset:10432
	v_cvt_pk_bf16_f32 v125, v126, v127
	v_cvt_pk_bf16_f32 v126, v128, v129
	v_cvt_pk_bf16_f32 v127, v130, v131
	s_waitcnt lgkmcnt(2)
; #define MFMA32(a, b, c) __builtin_amdgcn_mfma_f32_32x32x16_bf16((a), (b), (c), 0, 0, 0)
; template <int DK, int DV, int MODE, int QB, bool PACK = false>
; DI void attn_item(const AttArgs& a, int q0, int t_lo, int t_hi) {
;     ...
;   for (int tile = t_lo; tile < t_hi; ++tile) {
;     const int buf = (tile - t_lo) & 1;
;     if (tile + 1 < t_hi) att_swrite<DK, DV>(buf ^ 1, kr, vr);
;     if (tile + 2 < t_hi) att_gload<DK, DV, MODE>(a, tile + 2, kr, vr);
;     const unsigned char* Kb = smem + buf * BUFB;
;     ...
; #pragma unroll
;             for (int d = 0; d < NDB; ++d) {
;               s16x4 lo = __builtin_amdgcn_ds_read_tr16_b64_v4i16((s16x4 __attribute__((address_space(3)))*)(vrow + d * 64));
;               s16x4 hi = __builtin_amdgcn_ds_read_tr16_b64_v4i16((s16x4 __attribute__((address_space(3)))*)(vrow + 8 * VST + d * 64));
;               const bf16x8 vf = __builtin_shufflevector(lo, hi, 0, 1, 2, 3, 4, 5, 6, 7);
;               o[qb][d] = MFMA32(vf, pf, o[qb][d]);
;             }
;           }
;     }
;     __syncthreads();
;   }
	v_mfma_f32_32x32x16_bf16 v[64:79], v[8:11], v[12:15], v[64:79]
	ds_read_b64_tr_b16 v[80:81], v209 offset:11520
	ds_read_b64_tr_b16 v[82:83], v209 offset:12672
	v_cvt_pk_bf16_f32 v84, v196, v197
	v_cvt_pk_bf16_f32 v85, v198, v199
	v_cvt_pk_bf16_f32 v86, v200, v201
	v_cvt_pk_bf16_f32 v87, v202, v203
	v_cvt_pk_bf16_f32 v92, v140, v141
	v_cvt_pk_bf16_f32 v93, v142, v143
	s_waitcnt lgkmcnt(2)
	v_mfma_f32_32x32x16_bf16 v[48:63], v[4:7], v[12:15], v[48:63]
	ds_read_b64_tr_b16 v[12:13], v209 offset:11584
	ds_read_b64_tr_b16 v[14:15], v209 offset:12736
	ds_read_b64_tr_b16 v[88:89], v209 offset:13824
	ds_read_b64_tr_b16 v[90:91], v209 offset:14976
	v_cvt_pk_bf16_f32 v94, v192, v193
	v_cvt_pk_bf16_f32 v95, v194, v195
	v_cvt_pk_bf16_f32 v133, v134, v135
	v_cvt_pk_bf16_f32 v134, v136, v137
	v_cvt_pk_bf16_f32 v135, v138, v139
	v_mfma_f32_32x32x16_bf16 v[32:47], v[8:11], v[124:127], v[32:47]
	s_add_i32 s9, s9, 1
	s_add_u32 s4, s4, 0x40000
	s_addc_u32 s5, s5, 0
	s_cmp_eq_u32 s9, 31
	v_mfma_f32_32x32x16_bf16 v[16:31], v[4:7], v[124:127], v[16:31]
	v_cvt_pk_bf16_f32 v4, v116, v117
	v_cvt_pk_bf16_f32 v5, v118, v119
	v_cvt_pk_bf16_f32 v6, v120, v121
	v_cvt_pk_bf16_f32 v7, v122, v123
	s_waitcnt lgkmcnt(4)
	v_mfma_f32_32x32x16_bf16 v[64:79], v[80:83], v[84:87], v[64:79]
	s_waitcnt lgkmcnt(2)
	v_mfma_f32_32x32x16_bf16 v[48:63], v[12:15], v[84:87], v[48:63]
	ds_read_b64_tr_b16 v[84:85], v209 offset:13888
	ds_read_b64_tr_b16 v[86:87], v209 offset:15040
	ds_read_b64_tr_b16 v[96:97], v209 offset:16128
	ds_read_b64_tr_b16 v[98:99], v209 offset:17280
	v_mfma_f32_32x32x16_bf16 v[32:47], v[80:83], v[4:7], v[32:47]
	v_mfma_f32_32x32x16_bf16 v[16:31], v[12:15], v[4:7], v[16:31]
	v_cvt_pk_bf16_f32 v4, v108, v109
	v_cvt_pk_bf16_f32 v5, v110, v111
	v_cvt_pk_bf16_f32 v6, v112, v113
	v_cvt_pk_bf16_f32 v7, v114, v115
	s_waitcnt lgkmcnt(4)
	v_mfma_f32_32x32x16_bf16 v[64:79], v[88:91], v[92:95], v[64:79]
	s_waitcnt lgkmcnt(2)
	v_mfma_f32_32x32x16_bf16 v[48:63], v[84:87], v[92:95], v[48:63]
	ds_read_b64_tr_b16 v[92:93], v209 offset:16192
	ds_read_b64_tr_b16 v[94:95], v209 offset:17344
	s_waitcnt lgkmcnt(0)
	s_barrier
	v_mfma_f32_32x32x16_bf16 v[32:47], v[88:91], v[4:7], v[32:47]
	v_mfma_f32_32x32x16_bf16 v[16:31], v[84:87], v[4:7], v[16:31]
	v_cvt_pk_bf16_f32 v4, v100, v101
	v_cvt_pk_bf16_f32 v5, v102, v103
	v_cvt_pk_bf16_f32 v6, v104, v105
	v_cvt_pk_bf16_f32 v7, v106, v107
	v_mfma_f32_32x32x16_bf16 v[64:79], v[96:99], v[132:135], v[64:79]
	v_mfma_f32_32x32x16_bf16 v[48:63], v[92:95], v[132:135], v[48:63]
	v_mfma_f32_32x32x16_bf16 v[32:47], v[96:99], v[4:7], v[32:47]
	v_mfma_f32_32x32x16_bf16 v[16:31], v[92:95], v[4:7], v[16:31]
	s_cbranch_scc1 .LBB0_846
.LBB0_836:
	s_and_b32 s13, s9, 1
	s_xor_b32 s6, s13, 1
	s_mul_i32 s14, s6, 0x4800
	v_add_u32_e32 v211, s14, v210
	s_cmp_gt_u32 s9, 29
	s_waitcnt vmcnt(1)
	ds_write_b128 v211, v[176:179]
	s_cbranch_scc1 .LBB0_842
	global_load_dwordx4 v[176:179], v212, s[4:5] offset:1024

; template <int DK, int DV, int MODE, int QB, bool PACK = false>
; DI void attn_item(const AttArgs& a, int q0, int t_lo, int t_hi) {
;     ...
;     }
;     __syncthreads();
;   }
; #pragma unroll
;   for (int qb = 0; qb < QB; ++qb) {
;     float lt = lsum[qb] + __shfl_xor(lsum[qb], 32);
.LBB0_846:
	v_readfirstlane_b32 s2, v224
	s_cmpk_gt_u32 s2, 0xff
	s_cbranch_scc1 .Lpp0_exit
	s_barrier
